# gating section: 8 gate loads issued up front, vmcnt(7) pipelined
# baseline (speedup 1.0000x reference)
.LBB0_339:
	v_mbcnt_lo_u32_b32 v0, -1, 0
	v_mbcnt_hi_u32_b32 v0, -1, v0
	s_or_b32 s34, s34, s84
	v_add_u32_e32 v11, s97, v0
	v_lshlrev_b32_e32 v0, 4, v0
	v_ashrrev_i32_e32 v4, 3, v11
	v_and_b32_e32 v144, 0x70, v0
	s_add_u32 s0, s30, s10
	v_ashrrev_i32_e32 v5, 31, v4
	v_add_u32_e32 v10, 0, v144
	s_addc_u32 s1, s31, 0
	v_lshl_add_u64 v[14:15], s[34:35], 0, v[4:5]
	v_mov_b64_e32 v[12:13], s[28:29]
	v_lshl_add_u64 v[8:9], s[0:1], 0, v[144:145]
	v_mad_u64_u32 v[0:1], s[0:1], v4, s76, v[10:11]
	v_mad_u64_u32 v[4:5], s[0:1], v14, s75, v[12:13]
	v_mad_i32_i24 v5, v15, s75, v5
	v_lshl_add_u64 v[4:5], v[4:5], 0, s[10:11]
	v_lshl_add_u64 v[4:5], v[4:5], 0, v[144:145]
	v_add_co_u32_e32 v4, vcc, s82, v4
	s_mov_b32 s14, 0xc0000
	s_mov_b32 s15, 0
	v_addc_co_u32_e32 v5, vcc, 0, v5, vcc
	v_lshlrev_b64 v[6:7], 12, v[14:15]
	v_lshl_add_u64 v[6:7], v[8:9], 0, v[6:7]
	s_mov_b32 s18, 0x40000
	s_mov_b32 s19, 0
	ds_read_b128 v[80:83], v0
	ds_read_b128 v[84:87], v0 offset:9216
	ds_read_b128 v[88:91], v0 offset:18432
	ds_read_b128 v[92:95], v0 offset:27648
	ds_read_b128 v[96:99], v0 offset:36864
	ds_read_b128 v[100:103], v0 offset:46080
	ds_read_b128 v[104:107], v0 offset:55296
	ds_read_b128 v[108:111], v0 offset:64512
	global_load_dwordx4 v[112:115], v[4:5], off offset:2048 nt
	v_lshl_add_u64 v[4:5], v[4:5], 0, s[14:15]
	global_load_dwordx4 v[116:119], v[4:5], off offset:2048 nt
	v_lshl_add_u64 v[4:5], v[4:5], 0, s[14:15]
	global_load_dwordx4 v[120:123], v[4:5], off offset:2048 nt
	v_lshl_add_u64 v[4:5], v[4:5], 0, s[14:15]
	global_load_dwordx4 v[124:127], v[4:5], off offset:2048 nt
	v_lshl_add_u64 v[4:5], v[4:5], 0, s[14:15]
	global_load_dwordx4 v[128:131], v[4:5], off offset:2048 nt
	v_lshl_add_u64 v[4:5], v[4:5], 0, s[14:15]
	global_load_dwordx4 v[132:135], v[4:5], off offset:2048 nt
	v_lshl_add_u64 v[4:5], v[4:5], 0, s[14:15]
	global_load_dwordx4 v[48:51], v[4:5], off offset:2048 nt
	v_lshl_add_u64 v[4:5], v[4:5], 0, s[14:15]
	global_load_dwordx4 v[52:55], v[4:5], off offset:2048 nt
	s_waitcnt lgkmcnt(0)
	s_waitcnt vmcnt(7)
	v_lshlrev_b32_e32 v20, 16, v80
	v_and_b32_e32 v21, 0xffff0000, v80
	v_lshlrev_b32_e32 v16, 16, v112
	v_and_b32_e32 v17, 0xffff0000, v112
	v_mul_f32_e32 v22, 0xbfb8aa3b, v16
	v_mul_f32_e32 v23, 0xbfb8aa3b, v17
	v_exp_f32_e32 v22, v22
	v_exp_f32_e32 v23, v23
	s_nop 0
	v_add_f32_e32 v22, 1.0, v22
	v_add_f32_e32 v23, 1.0, v23
	v_rcp_f32_e32 v18, v22
	v_rcp_f32_e32 v19, v23
	s_nop 1
	v_pk_mul_f32 v[16:17], v[18:19], v[16:17]
	s_nop 0
	v_pk_mul_f32 v[16:17], v[16:17], v[20:21]
	s_nop 0
	v_cvt_pk_bf16_f32 v0, v16, v17
	v_lshlrev_b32_e32 v20, 16, v81
	v_and_b32_e32 v21, 0xffff0000, v81
	v_lshlrev_b32_e32 v16, 16, v113
	v_and_b32_e32 v17, 0xffff0000, v113
	v_mul_f32_e32 v22, 0xbfb8aa3b, v16
	v_mul_f32_e32 v23, 0xbfb8aa3b, v17
	v_exp_f32_e32 v22, v22
	v_exp_f32_e32 v23, v23
	s_nop 0
	v_add_f32_e32 v22, 1.0, v22
	v_add_f32_e32 v23, 1.0, v23
	v_rcp_f32_e32 v18, v22
	v_rcp_f32_e32 v19, v23
	s_nop 1
	v_pk_mul_f32 v[16:17], v[18:19], v[16:17]
	s_nop 0
	v_pk_mul_f32 v[16:17], v[16:17], v[20:21]
	s_nop 0
	v_cvt_pk_bf16_f32 v1, v16, v17
	v_lshlrev_b32_e32 v20, 16, v82
	v_and_b32_e32 v21, 0xffff0000, v82
	v_lshlrev_b32_e32 v16, 16, v114
	v_and_b32_e32 v17, 0xffff0000, v114
	v_mul_f32_e32 v22, 0xbfb8aa3b, v16
	v_mul_f32_e32 v23, 0xbfb8aa3b, v17
	v_exp_f32_e32 v22, v22
	v_exp_f32_e32 v23, v23
	s_nop 0
	v_add_f32_e32 v22, 1.0, v22
	v_add_f32_e32 v23, 1.0, v23
	v_rcp_f32_e32 v18, v22
	v_rcp_f32_e32 v19, v23
	s_nop 1
	v_pk_mul_f32 v[16:17], v[18:19], v[16:17]
	s_nop 0
	v_pk_mul_f32 v[16:17], v[16:17], v[20:21]
	s_nop 0
	v_cvt_pk_bf16_f32 v2, v16, v17
	v_lshlrev_b32_e32 v20, 16, v83
	v_and_b32_e32 v21, 0xffff0000, v83
	v_lshlrev_b32_e32 v16, 16, v115
	v_and_b32_e32 v17, 0xffff0000, v115
	v_mul_f32_e32 v22, 0xbfb8aa3b, v16
	v_mul_f32_e32 v23, 0xbfb8aa3b, v17
	v_exp_f32_e32 v22, v22
	v_exp_f32_e32 v23, v23
	s_nop 0
	v_add_f32_e32 v22, 1.0, v22
	v_add_f32_e32 v23, 1.0, v23
	v_rcp_f32_e32 v18, v22
	v_rcp_f32_e32 v19, v23
	s_nop 1
	v_pk_mul_f32 v[16:17], v[18:19], v[16:17]
	s_nop 0
	v_pk_mul_f32 v[16:17], v[16:17], v[20:21]
	s_nop 0
	v_cvt_pk_bf16_f32 v3, v16, v17
	s_nop 0
	global_store_dwordx4 v[6:7], v[0:3], off
	s_waitcnt vmcnt(7)
	v_lshl_add_u64 v[6:7], v[6:7], 0, s[18:19]
	v_lshlrev_b32_e32 v20, 16, v84
	v_and_b32_e32 v21, 0xffff0000, v84
	v_lshlrev_b32_e32 v16, 16, v116
	v_and_b32_e32 v17, 0xffff0000, v116
	v_mul_f32_e32 v22, 0xbfb8aa3b, v16
	v_mul_f32_e32 v23, 0xbfb8aa3b, v17
	v_exp_f32_e32 v22, v22
	v_exp_f32_e32 v23, v23
	s_nop 0
	v_add_f32_e32 v22, 1.0, v22
	v_add_f32_e32 v23, 1.0, v23
	v_rcp_f32_e32 v18, v22
	v_rcp_f32_e32 v19, v23
	s_nop 1
	v_pk_mul_f32 v[16:17], v[18:19], v[16:17]
	s_nop 0
	v_pk_mul_f32 v[16:17], v[16:17], v[20:21]
	s_nop 0
	v_cvt_pk_bf16_f32 v24, v16, v17
	v_lshlrev_b32_e32 v20, 16, v85
	v_and_b32_e32 v21, 0xffff0000, v85
	v_lshlrev_b32_e32 v16, 16, v117
	v_and_b32_e32 v17, 0xffff0000, v117
	v_mul_f32_e32 v22, 0xbfb8aa3b, v16
	v_mul_f32_e32 v23, 0xbfb8aa3b, v17
	v_exp_f32_e32 v22, v22
	v_exp_f32_e32 v23, v23
	s_nop 0
	v_add_f32_e32 v22, 1.0, v22
	v_add_f32_e32 v23, 1.0, v23
	v_rcp_f32_e32 v18, v22
	v_rcp_f32_e32 v19, v23
	s_nop 1
	v_pk_mul_f32 v[16:17], v[18:19], v[16:17]
	s_nop 0
	v_pk_mul_f32 v[16:17], v[16:17], v[20:21]
	s_nop 0
	v_cvt_pk_bf16_f32 v25, v16, v17
	v_lshlrev_b32_e32 v20, 16, v86
	v_and_b32_e32 v21, 0xffff0000, v86
	v_lshlrev_b32_e32 v16, 16, v118
	v_and_b32_e32 v17, 0xffff0000, v118
	v_mul_f32_e32 v22, 0xbfb8aa3b, v16
	v_mul_f32_e32 v23, 0xbfb8aa3b, v17
	v_exp_f32_e32 v22, v22
	v_exp_f32_e32 v23, v23
	s_nop 0
	v_add_f32_e32 v22, 1.0, v22
	v_add_f32_e32 v23, 1.0, v23
	v_rcp_f32_e32 v18, v22
	v_rcp_f32_e32 v19, v23
	s_nop 1
	v_pk_mul_f32 v[16:17], v[18:19], v[16:17]
	s_nop 0
	v_pk_mul_f32 v[16:17], v[16:17], v[20:21]
	s_nop 0
	v_cvt_pk_bf16_f32 v26, v16, v17
	v_lshlrev_b32_e32 v20, 16, v87
	v_and_b32_e32 v21, 0xffff0000, v87
	v_lshlrev_b32_e32 v16, 16, v119
	v_and_b32_e32 v17, 0xffff0000, v119
	v_mul_f32_e32 v22, 0xbfb8aa3b, v16
	v_mul_f32_e32 v23, 0xbfb8aa3b, v17
	v_exp_f32_e32 v22, v22
	v_exp_f32_e32 v23, v23
	s_nop 0
	v_add_f32_e32 v22, 1.0, v22
	v_add_f32_e32 v23, 1.0, v23
	v_rcp_f32_e32 v18, v22
	v_rcp_f32_e32 v19, v23
	s_nop 1
	v_pk_mul_f32 v[16:17], v[18:19], v[16:17]
	s_nop 0
	v_pk_mul_f32 v[16:17], v[16:17], v[20:21]
	s_nop 0
	v_cvt_pk_bf16_f32 v27, v16, v17
	s_nop 0
	global_store_dwordx4 v[6:7], v[24:27], off
	s_waitcnt vmcnt(7)
	v_lshl_add_u64 v[6:7], v[6:7], 0, s[18:19]
	v_lshlrev_b32_e32 v20, 16, v88
	v_and_b32_e32 v21, 0xffff0000, v88
	v_lshlrev_b32_e32 v16, 16, v120
	v_and_b32_e32 v17, 0xffff0000, v120
	v_mul_f32_e32 v22, 0xbfb8aa3b, v16
	v_mul_f32_e32 v23, 0xbfb8aa3b, v17
	v_exp_f32_e32 v22, v22
	v_exp_f32_e32 v23, v23
	s_nop 0
	v_add_f32_e32 v22, 1.0, v22
	v_add_f32_e32 v23, 1.0, v23
	v_rcp_f32_e32 v18, v22
	v_rcp_f32_e32 v19, v23
	s_nop 1
	v_pk_mul_f32 v[16:17], v[18:19], v[16:17]
	s_nop 0
	v_pk_mul_f32 v[16:17], v[16:17], v[20:21]
	s_nop 0
	v_cvt_pk_bf16_f32 v0, v16, v17
	v_lshlrev_b32_e32 v20, 16, v89
	v_and_b32_e32 v21, 0xffff0000, v89
	v_lshlrev_b32_e32 v16, 16, v121
	v_and_b32_e32 v17, 0xffff0000, v121
	v_mul_f32_e32 v22, 0xbfb8aa3b, v16
	v_mul_f32_e32 v23, 0xbfb8aa3b, v17
	v_exp_f32_e32 v22, v22
	v_exp_f32_e32 v23, v23
	s_nop 0
	v_add_f32_e32 v22, 1.0, v22
	v_add_f32_e32 v23, 1.0, v23
	v_rcp_f32_e32 v18, v22
	v_rcp_f32_e32 v19, v23
	s_nop 1
	v_pk_mul_f32 v[16:17], v[18:19], v[16:17]
	s_nop 0
	v_pk_mul_f32 v[16:17], v[16:17], v[20:21]
	s_nop 0
	v_cvt_pk_bf16_f32 v1, v16, v17
	v_lshlrev_b32_e32 v20, 16, v90
	v_and_b32_e32 v21, 0xffff0000, v90
	v_lshlrev_b32_e32 v16, 16, v122
	v_and_b32_e32 v17, 0xffff0000, v122
	v_mul_f32_e32 v22, 0xbfb8aa3b, v16
	v_mul_f32_e32 v23, 0xbfb8aa3b, v17
	v_exp_f32_e32 v22, v22
	v_exp_f32_e32 v23, v23
	s_nop 0
	v_add_f32_e32 v22, 1.0, v22
	v_add_f32_e32 v23, 1.0, v23
	v_rcp_f32_e32 v18, v22
	v_rcp_f32_e32 v19, v23
	s_nop 1
	v_pk_mul_f32 v[16:17], v[18:19], v[16:17]
	s_nop 0
	v_pk_mul_f32 v[16:17], v[16:17], v[20:21]
	s_nop 0
	v_cvt_pk_bf16_f32 v2, v16, v17
	v_lshlrev_b32_e32 v20, 16, v91
	v_and_b32_e32 v21, 0xffff0000, v91
	v_lshlrev_b32_e32 v16, 16, v123
	v_and_b32_e32 v17, 0xffff0000, v123
	v_mul_f32_e32 v22, 0xbfb8aa3b, v16
	v_mul_f32_e32 v23, 0xbfb8aa3b, v17
	v_exp_f32_e32 v22, v22
	v_exp_f32_e32 v23, v23
	s_nop 0
	v_add_f32_e32 v22, 1.0, v22
	v_add_f32_e32 v23, 1.0, v23
	v_rcp_f32_e32 v18, v22
	v_rcp_f32_e32 v19, v23
	s_nop 1
	v_pk_mul_f32 v[16:17], v[18:19], v[16:17]
	s_nop 0
	v_pk_mul_f32 v[16:17], v[16:17], v[20:21]
	s_nop 0
	v_cvt_pk_bf16_f32 v3, v16, v17
	s_nop 0
	global_store_dwordx4 v[6:7], v[0:3], off
	s_waitcnt vmcnt(7)
	v_lshl_add_u64 v[6:7], v[6:7], 0, s[18:19]
	v_lshlrev_b32_e32 v20, 16, v92
	v_and_b32_e32 v21, 0xffff0000, v92
	v_lshlrev_b32_e32 v16, 16, v124
	v_and_b32_e32 v17, 0xffff0000, v124
	v_mul_f32_e32 v22, 0xbfb8aa3b, v16
	v_mul_f32_e32 v23, 0xbfb8aa3b, v17
	v_exp_f32_e32 v22, v22
	v_exp_f32_e32 v23, v23
	s_nop 0
	v_add_f32_e32 v22, 1.0, v22
	v_add_f32_e32 v23, 1.0, v23
	v_rcp_f32_e32 v18, v22
	v_rcp_f32_e32 v19, v23
	s_nop 1
	v_pk_mul_f32 v[16:17], v[18:19], v[16:17]
	s_nop 0
	v_pk_mul_f32 v[16:17], v[16:17], v[20:21]
	s_nop 0
	v_cvt_pk_bf16_f32 v24, v16, v17
	v_lshlrev_b32_e32 v20, 16, v93
	v_and_b32_e32 v21, 0xffff0000, v93
	v_lshlrev_b32_e32 v16, 16, v125
	v_and_b32_e32 v17, 0xffff0000, v125
	v_mul_f32_e32 v22, 0xbfb8aa3b, v16
	v_mul_f32_e32 v23, 0xbfb8aa3b, v17
	v_exp_f32_e32 v22, v22
	v_exp_f32_e32 v23, v23
	s_nop 0
	v_add_f32_e32 v22, 1.0, v22
	v_add_f32_e32 v23, 1.0, v23
	v_rcp_f32_e32 v18, v22
	v_rcp_f32_e32 v19, v23
	s_nop 1
	v_pk_mul_f32 v[16:17], v[18:19], v[16:17]
	s_nop 0
	v_pk_mul_f32 v[16:17], v[16:17], v[20:21]
	s_nop 0
	v_cvt_pk_bf16_f32 v25, v16, v17
	v_lshlrev_b32_e32 v20, 16, v94
	v_and_b32_e32 v21, 0xffff0000, v94
	v_lshlrev_b32_e32 v16, 16, v126
	v_and_b32_e32 v17, 0xffff0000, v126
	v_mul_f32_e32 v22, 0xbfb8aa3b, v16
	v_mul_f32_e32 v23, 0xbfb8aa3b, v17
	v_exp_f32_e32 v22, v22
	v_exp_f32_e32 v23, v23
	s_nop 0
	v_add_f32_e32 v22, 1.0, v22
	v_add_f32_e32 v23, 1.0, v23
	v_rcp_f32_e32 v18, v22
	v_rcp_f32_e32 v19, v23
	s_nop 1
	v_pk_mul_f32 v[16:17], v[18:19], v[16:17]
	s_nop 0
	v_pk_mul_f32 v[16:17], v[16:17], v[20:21]
	s_nop 0
	v_cvt_pk_bf16_f32 v26, v16, v17
	v_lshlrev_b32_e32 v20, 16, v95
	v_and_b32_e32 v21, 0xffff0000, v95
	v_lshlrev_b32_e32 v16, 16, v127
	v_and_b32_e32 v17, 0xffff0000, v127
	v_mul_f32_e32 v22, 0xbfb8aa3b, v16
	v_mul_f32_e32 v23, 0xbfb8aa3b, v17
	v_exp_f32_e32 v22, v22
	v_exp_f32_e32 v23, v23
	s_nop 0
	v_add_f32_e32 v22, 1.0, v22
	v_add_f32_e32 v23, 1.0, v23
	v_rcp_f32_e32 v18, v22
	v_rcp_f32_e32 v19, v23
	s_nop 1
	v_pk_mul_f32 v[16:17], v[18:19], v[16:17]
	s_nop 0
	v_pk_mul_f32 v[16:17], v[16:17], v[20:21]
	s_nop 0
	v_cvt_pk_bf16_f32 v27, v16, v17
	s_nop 0
	global_store_dwordx4 v[6:7], v[24:27], off
	s_waitcnt vmcnt(7)
	v_lshl_add_u64 v[6:7], v[6:7], 0, s[18:19]
	v_lshlrev_b32_e32 v20, 16, v96
	v_and_b32_e32 v21, 0xffff0000, v96
	v_lshlrev_b32_e32 v16, 16, v128
	v_and_b32_e32 v17, 0xffff0000, v128
	v_mul_f32_e32 v22, 0xbfb8aa3b, v16
	v_mul_f32_e32 v23, 0xbfb8aa3b, v17
	v_exp_f32_e32 v22, v22
	v_exp_f32_e32 v23, v23
	s_nop 0
	v_add_f32_e32 v22, 1.0, v22
	v_add_f32_e32 v23, 1.0, v23
	v_rcp_f32_e32 v18, v22
	v_rcp_f32_e32 v19, v23
	s_nop 1
	v_pk_mul_f32 v[16:17], v[18:19], v[16:17]
	s_nop 0
	v_pk_mul_f32 v[16:17], v[16:17], v[20:21]
	s_nop 0
	v_cvt_pk_bf16_f32 v0, v16, v17
	v_lshlrev_b32_e32 v20, 16, v97
	v_and_b32_e32 v21, 0xffff0000, v97
	v_lshlrev_b32_e32 v16, 16, v129
	v_and_b32_e32 v17, 0xffff0000, v129
	v_mul_f32_e32 v22, 0xbfb8aa3b, v16
	v_mul_f32_e32 v23, 0xbfb8aa3b, v17
	v_exp_f32_e32 v22, v22
	v_exp_f32_e32 v23, v23
	s_nop 0
	v_add_f32_e32 v22, 1.0, v22
	v_add_f32_e32 v23, 1.0, v23
	v_rcp_f32_e32 v18, v22
	v_rcp_f32_e32 v19, v23
	s_nop 1
	v_pk_mul_f32 v[16:17], v[18:19], v[16:17]
	s_nop 0
	v_pk_mul_f32 v[16:17], v[16:17], v[20:21]
	s_nop 0
	v_cvt_pk_bf16_f32 v1, v16, v17
	v_lshlrev_b32_e32 v20, 16, v98
	v_and_b32_e32 v21, 0xffff0000, v98
	v_lshlrev_b32_e32 v16, 16, v130
	v_and_b32_e32 v17, 0xffff0000, v130
	v_mul_f32_e32 v22, 0xbfb8aa3b, v16
	v_mul_f32_e32 v23, 0xbfb8aa3b, v17
	v_exp_f32_e32 v22, v22
	v_exp_f32_e32 v23, v23
	s_nop 0
	v_add_f32_e32 v22, 1.0, v22
	v_add_f32_e32 v23, 1.0, v23
	v_rcp_f32_e32 v18, v22
	v_rcp_f32_e32 v19, v23
	s_nop 1
	v_pk_mul_f32 v[16:17], v[18:19], v[16:17]
	s_nop 0
	v_pk_mul_f32 v[16:17], v[16:17], v[20:21]
	s_nop 0
	v_cvt_pk_bf16_f32 v2, v16, v17
	v_lshlrev_b32_e32 v20, 16, v99
	v_and_b32_e32 v21, 0xffff0000, v99
	v_lshlrev_b32_e32 v16, 16, v131
	v_and_b32_e32 v17, 0xffff0000, v131
	v_mul_f32_e32 v22, 0xbfb8aa3b, v16
	v_mul_f32_e32 v23, 0xbfb8aa3b, v17
	v_exp_f32_e32 v22, v22
	v_exp_f32_e32 v23, v23
	s_nop 0
	v_add_f32_e32 v22, 1.0, v22
	v_add_f32_e32 v23, 1.0, v23
	v_rcp_f32_e32 v18, v22
	v_rcp_f32_e32 v19, v23
	s_nop 1
	v_pk_mul_f32 v[16:17], v[18:19], v[16:17]
	s_nop 0
	v_pk_mul_f32 v[16:17], v[16:17], v[20:21]
	s_nop 0
	v_cvt_pk_bf16_f32 v3, v16, v17
	s_nop 0
	global_store_dwordx4 v[6:7], v[0:3], off
	s_waitcnt vmcnt(7)
	v_lshl_add_u64 v[6:7], v[6:7], 0, s[18:19]
	v_lshlrev_b32_e32 v20, 16, v100
	v_and_b32_e32 v21, 0xffff0000, v100
	v_lshlrev_b32_e32 v16, 16, v132
	v_and_b32_e32 v17, 0xffff0000, v132
	v_mul_f32_e32 v22, 0xbfb8aa3b, v16
	v_mul_f32_e32 v23, 0xbfb8aa3b, v17
	v_exp_f32_e32 v22, v22
	v_exp_f32_e32 v23, v23
	s_nop 0
	v_add_f32_e32 v22, 1.0, v22
	v_add_f32_e32 v23, 1.0, v23
	v_rcp_f32_e32 v18, v22
	v_rcp_f32_e32 v19, v23
	s_nop 1
	v_pk_mul_f32 v[16:17], v[18:19], v[16:17]
	s_nop 0
	v_pk_mul_f32 v[16:17], v[16:17], v[20:21]
	s_nop 0
	v_cvt_pk_bf16_f32 v24, v16, v17
	v_lshlrev_b32_e32 v20, 16, v101
	v_and_b32_e32 v21, 0xffff0000, v101
	v_lshlrev_b32_e32 v16, 16, v133
	v_and_b32_e32 v17, 0xffff0000, v133
	v_mul_f32_e32 v22, 0xbfb8aa3b, v16
	v_mul_f32_e32 v23, 0xbfb8aa3b, v17
	v_exp_f32_e32 v22, v22
	v_exp_f32_e32 v23, v23
	s_nop 0
	v_add_f32_e32 v22, 1.0, v22
	v_add_f32_e32 v23, 1.0, v23
	v_rcp_f32_e32 v18, v22
	v_rcp_f32_e32 v19, v23
	s_nop 1
	v_pk_mul_f32 v[16:17], v[18:19], v[16:17]
	s_nop 0
	v_pk_mul_f32 v[16:17], v[16:17], v[20:21]
	s_nop 0
	v_cvt_pk_bf16_f32 v25, v16, v17
	v_lshlrev_b32_e32 v20, 16, v102
	v_and_b32_e32 v21, 0xffff0000, v102
	v_lshlrev_b32_e32 v16, 16, v134
	v_and_b32_e32 v17, 0xffff0000, v134
	v_mul_f32_e32 v22, 0xbfb8aa3b, v16
	v_mul_f32_e32 v23, 0xbfb8aa3b, v17
	v_exp_f32_e32 v22, v22
	v_exp_f32_e32 v23, v23
	s_nop 0
	v_add_f32_e32 v22, 1.0, v22
	v_add_f32_e32 v23, 1.0, v23
	v_rcp_f32_e32 v18, v22
	v_rcp_f32_e32 v19, v23
	s_nop 1
	v_pk_mul_f32 v[16:17], v[18:19], v[16:17]
	s_nop 0
	v_pk_mul_f32 v[16:17], v[16:17], v[20:21]
	s_nop 0
	v_cvt_pk_bf16_f32 v26, v16, v17
	v_lshlrev_b32_e32 v20, 16, v103
	v_and_b32_e32 v21, 0xffff0000, v103
	v_lshlrev_b32_e32 v16, 16, v135
	v_and_b32_e32 v17, 0xffff0000, v135
	v_mul_f32_e32 v22, 0xbfb8aa3b, v16
	v_mul_f32_e32 v23, 0xbfb8aa3b, v17
	v_exp_f32_e32 v22, v22
	v_exp_f32_e32 v23, v23
	s_nop 0
	v_add_f32_e32 v22, 1.0, v22
	v_add_f32_e32 v23, 1.0, v23
	v_rcp_f32_e32 v18, v22
	v_rcp_f32_e32 v19, v23
	s_nop 1
	v_pk_mul_f32 v[16:17], v[18:19], v[16:17]
	s_nop 0
	v_pk_mul_f32 v[16:17], v[16:17], v[20:21]
	s_nop 0
	v_cvt_pk_bf16_f32 v27, v16, v17
	s_nop 0
	global_store_dwordx4 v[6:7], v[24:27], off
	s_waitcnt vmcnt(7)
	v_lshl_add_u64 v[6:7], v[6:7], 0, s[18:19]
	v_lshlrev_b32_e32 v20, 16, v104
	v_and_b32_e32 v21, 0xffff0000, v104
	v_lshlrev_b32_e32 v16, 16, v48
	v_and_b32_e32 v17, 0xffff0000, v48
	v_mul_f32_e32 v22, 0xbfb8aa3b, v16
	v_mul_f32_e32 v23, 0xbfb8aa3b, v17
	v_exp_f32_e32 v22, v22
	v_exp_f32_e32 v23, v23
	s_nop 0
	v_add_f32_e32 v22, 1.0, v22
	v_add_f32_e32 v23, 1.0, v23
	v_rcp_f32_e32 v18, v22
	v_rcp_f32_e32 v19, v23
	s_nop 1
	v_pk_mul_f32 v[16:17], v[18:19], v[16:17]
	s_nop 0
	v_pk_mul_f32 v[16:17], v[16:17], v[20:21]
	s_nop 0
	v_cvt_pk_bf16_f32 v0, v16, v17
	v_lshlrev_b32_e32 v20, 16, v105
	v_and_b32_e32 v21, 0xffff0000, v105
	v_lshlrev_b32_e32 v16, 16, v49
	v_and_b32_e32 v17, 0xffff0000, v49
	v_mul_f32_e32 v22, 0xbfb8aa3b, v16
	v_mul_f32_e32 v23, 0xbfb8aa3b, v17
	v_exp_f32_e32 v22, v22
	v_exp_f32_e32 v23, v23
	s_nop 0
	v_add_f32_e32 v22, 1.0, v22
	v_add_f32_e32 v23, 1.0, v23
	v_rcp_f32_e32 v18, v22
	v_rcp_f32_e32 v19, v23
	s_nop 1
	v_pk_mul_f32 v[16:17], v[18:19], v[16:17]
	s_nop 0
	v_pk_mul_f32 v[16:17], v[16:17], v[20:21]
	s_nop 0
	v_cvt_pk_bf16_f32 v1, v16, v17
	v_lshlrev_b32_e32 v20, 16, v106
	v_and_b32_e32 v21, 0xffff0000, v106
	v_lshlrev_b32_e32 v16, 16, v50
	v_and_b32_e32 v17, 0xffff0000, v50
	v_mul_f32_e32 v22, 0xbfb8aa3b, v16
	v_mul_f32_e32 v23, 0xbfb8aa3b, v17
	v_exp_f32_e32 v22, v22
	v_exp_f32_e32 v23, v23
	s_nop 0
	v_add_f32_e32 v22, 1.0, v22
	v_add_f32_e32 v23, 1.0, v23
	v_rcp_f32_e32 v18, v22
	v_rcp_f32_e32 v19, v23
	s_nop 1
	v_pk_mul_f32 v[16:17], v[18:19], v[16:17]
	s_nop 0
	v_pk_mul_f32 v[16:17], v[16:17], v[20:21]
	s_nop 0
	v_cvt_pk_bf16_f32 v2, v16, v17
	v_lshlrev_b32_e32 v20, 16, v107
	v_and_b32_e32 v21, 0xffff0000, v107
	v_lshlrev_b32_e32 v16, 16, v51
	v_and_b32_e32 v17, 0xffff0000, v51
	v_mul_f32_e32 v22, 0xbfb8aa3b, v16
	v_mul_f32_e32 v23, 0xbfb8aa3b, v17
	v_exp_f32_e32 v22, v22
	v_exp_f32_e32 v23, v23
	s_nop 0
	v_add_f32_e32 v22, 1.0, v22
	v_add_f32_e32 v23, 1.0, v23
	v_rcp_f32_e32 v18, v22
	v_rcp_f32_e32 v19, v23
	s_nop 1
	v_pk_mul_f32 v[16:17], v[18:19], v[16:17]
	s_nop 0
	v_pk_mul_f32 v[16:17], v[16:17], v[20:21]
	s_nop 0
	v_cvt_pk_bf16_f32 v3, v16, v17
	s_nop 0
	global_store_dwordx4 v[6:7], v[0:3], off
	s_waitcnt vmcnt(7)
	v_lshl_add_u64 v[6:7], v[6:7], 0, s[18:19]
	v_lshlrev_b32_e32 v20, 16, v108
	v_and_b32_e32 v21, 0xffff0000, v108
	v_lshlrev_b32_e32 v16, 16, v52
	v_and_b32_e32 v17, 0xffff0000, v52
	v_mul_f32_e32 v22, 0xbfb8aa3b, v16
	v_mul_f32_e32 v23, 0xbfb8aa3b, v17
	v_exp_f32_e32 v22, v22
	v_exp_f32_e32 v23, v23
	s_nop 0
	v_add_f32_e32 v22, 1.0, v22
	v_add_f32_e32 v23, 1.0, v23
	v_rcp_f32_e32 v18, v22
	v_rcp_f32_e32 v19, v23
	s_nop 1
	v_pk_mul_f32 v[16:17], v[18:19], v[16:17]
	s_nop 0
	v_pk_mul_f32 v[16:17], v[16:17], v[20:21]
	s_nop 0
	v_cvt_pk_bf16_f32 v24, v16, v17
	v_lshlrev_b32_e32 v20, 16, v109
	v_and_b32_e32 v21, 0xffff0000, v109
	v_lshlrev_b32_e32 v16, 16, v53
	v_and_b32_e32 v17, 0xffff0000, v53
	v_mul_f32_e32 v22, 0xbfb8aa3b, v16
	v_mul_f32_e32 v23, 0xbfb8aa3b, v17
	v_exp_f32_e32 v22, v22
	v_exp_f32_e32 v23, v23
	s_nop 0
	v_add_f32_e32 v22, 1.0, v22
	v_add_f32_e32 v23, 1.0, v23
	v_rcp_f32_e32 v18, v22
	v_rcp_f32_e32 v19, v23
	s_nop 1
	v_pk_mul_f32 v[16:17], v[18:19], v[16:17]
	s_nop 0
	v_pk_mul_f32 v[16:17], v[16:17], v[20:21]
	s_nop 0
	v_cvt_pk_bf16_f32 v25, v16, v17
	v_lshlrev_b32_e32 v20, 16, v110
	v_and_b32_e32 v21, 0xffff0000, v110
	v_lshlrev_b32_e32 v16, 16, v54
	v_and_b32_e32 v17, 0xffff0000, v54
	v_mul_f32_e32 v22, 0xbfb8aa3b, v16
	v_mul_f32_e32 v23, 0xbfb8aa3b, v17
	v_exp_f32_e32 v22, v22
	v_exp_f32_e32 v23, v23
	s_nop 0
	v_add_f32_e32 v22, 1.0, v22
	v_add_f32_e32 v23, 1.0, v23
	v_rcp_f32_e32 v18, v22
	v_rcp_f32_e32 v19, v23
	s_nop 1
	v_pk_mul_f32 v[16:17], v[18:19], v[16:17]
	s_nop 0
	v_pk_mul_f32 v[16:17], v[16:17], v[20:21]
	s_nop 0
	v_cvt_pk_bf16_f32 v26, v16, v17
	v_lshlrev_b32_e32 v20, 16, v111
	v_and_b32_e32 v21, 0xffff0000, v111
	v_lshlrev_b32_e32 v16, 16, v55
	v_and_b32_e32 v17, 0xffff0000, v55
	v_mul_f32_e32 v22, 0xbfb8aa3b, v16
	v_mul_f32_e32 v23, 0xbfb8aa3b, v17
	v_exp_f32_e32 v22, v22
	v_exp_f32_e32 v23, v23
	s_nop 0
	v_add_f32_e32 v22, 1.0, v22
	v_add_f32_e32 v23, 1.0, v23
	v_rcp_f32_e32 v18, v22
	v_rcp_f32_e32 v19, v23
	s_nop 1
	v_pk_mul_f32 v[16:17], v[18:19], v[16:17]
	s_nop 0
	v_pk_mul_f32 v[16:17], v[16:17], v[20:21]
	s_nop 0
	v_cvt_pk_bf16_f32 v27, v16, v17
	s_nop 0
	global_store_dwordx4 v[6:7], v[24:27], off
	s_add_i32 s83, s83, s94
	s_cmpk_gt_i32 s83, 0xff
	s_barrier
	s_cbranch_scc1 .LBB0_377
